# branch A: per-piece LayerNorm stat ds_reads hoisted to the group top (no LDS drain between the transposed ds_write_b16 bursts)
# baseline (speedup 1.0000x reference)
; __device__ __forceinline__ u32x4 pack8(const f32x4 a, const f32x4 b) { u32x4 w; w.x = cvt_pk_bf16(a[0], a[1]); w.y = cvt_pk_bf16(a[2], a[3]); w.z = cvt_pk_bf16(b[0], b[1]); w.w = cvt_pk_bf16(b[2], b[3]); return w; }
; #define LAS __attribute__((address_space(3)))
;     ...
;     for (int g = 0; g < 8; ++g) {
;         const f32x4 ga = *(const LAS f32x4*)(gbl + g * 128 + (tid & 15) * 8), gb2 = *(const LAS f32x4*)(gbl + g * 128 + (tid & 15) * 8 + 4);
;         const f32x4 ba = *(const LAS f32x4*)(gbl + 1024 + g * 128 + (tid & 15) * 8), bb2 = *(const LAS f32x4*)(gbl + 1024 + g * 128 + (tid & 15) * 8 + 4);
; #pragma unroll
;         for (int i = 0; i < 4; ++i) {
;             const int p = tid + 512 * i, s = p >> 4, dc = p & 15;
;             f32x4 v0, v1; pg8::unpack8(vpc[i], v0, v1);
;             const float mean = stat[s * 2], rstd = stat[s * 2 + 1];
;             v0 = (v0 - mean) * rstd * ga + ba; v1 = (v1 - mean) * rstd * gb2 + bb2;
;             const u32x4 w = pg8::pack8(v0, v1);
;             LAS unsigned short* dst = (LAS unsigned short*)(lds + BA_VNT) + dc * 136 + s;
;             dst[0 * 16 * 136] = (unsigned short)(w.x & 0xffffu); dst[1 * 16 * 136] = (unsigned short)(w.x >> 16); dst[2 * 16 * 136] = (unsigned short)(w.y & 0xffffu); dst[3 * 16 * 136] = (unsigned short)(w.y >> 16);
;             dst[4 * 16 * 136] = (unsigned short)(w.z & 0xffffu); dst[5 * 16 * 136] = (unsigned short)(w.z >> 16); dst[6 * 16 * 136] = (unsigned short)(w.w & 0xffffu); dst[7 * 16 * 136] = (unsigned short)(w.w >> 16);
;         }
.LBB0_510:
	ds_read_b128 v[8:11], v176
	ds_read_b128 v[0:3], v176 offset:16
	ds_read_b128 v[12:15], v176 offset:4096
	ds_read_b128 v[4:7], v176 offset:4112
	ds_read_b64 v[16:17], v177
	ds_read_b64 v[182:183], v173
	ds_read_b64 v[184:185], v171
	ds_read_b64 v[186:187], v169
	v_lshlrev_b32_e32 v20, 16, v126
	v_and_b32_e32 v21, 0xffff0000, v126
	v_lshlrev_b32_e32 v18, 16, v127
	v_and_b32_e32 v19, 0xffff0000, v127
	v_lshlrev_b32_e32 v24, 16, v128
	v_and_b32_e32 v25, 0xffff0000, v128
	v_lshlrev_b32_e32 v22, 16, v129
	v_and_b32_e32 v23, 0xffff0000, v129
	s_waitcnt lgkmcnt(0)
	v_sub_f32_e32 v21, v21, v16
	v_sub_f32_e32 v20, v20, v16
	v_sub_f32_e32 v19, v19, v16
	v_sub_f32_e32 v18, v18, v16
	v_pk_mul_f32 v[20:21], v[16:17], v[20:21] op_sel:[1,0]
	v_sub_f32_e32 v23, v23, v16
	v_sub_f32_e32 v22, v22, v16
	v_sub_f32_e32 v25, v25, v16
	v_sub_f32_e32 v24, v24, v16
	v_pk_mul_f32 v[18:19], v[16:17], v[18:19] op_sel:[1,0]
	v_pk_fma_f32 v[20:21], v[8:9], v[20:21], v[12:13]
	v_pk_mul_f32 v[24:25], v[16:17], v[24:25] op_sel:[1,0]
	v_pk_mul_f32 v[16:17], v[16:17], v[22:23] op_sel:[1,0]
	v_pk_fma_f32 v[18:19], v[10:11], v[18:19], v[14:15]
	v_pk_fma_f32 v[16:17], v[2:3], v[16:17], v[6:7]
	v_pk_fma_f32 v[22:23], v[0:1], v[24:25], v[4:5]
	v_cvt_pk_bf16_f32 v20, v20, v21
	v_cvt_pk_bf16_f32 v18, v18, v19
	v_cvt_pk_bf16_f32 v19, v22, v23
	v_cvt_pk_bf16_f32 v16, v16, v17
	ds_write_b16 v174, v20 offset:9216
	ds_write_b16_d16_hi v174, v20 offset:13568
	ds_write_b16 v174, v18 offset:17920
	ds_write_b16_d16_hi v174, v18 offset:22272
	ds_write_b16 v174, v19 offset:26624
	ds_write_b16_d16_hi v174, v19 offset:30976
	ds_write_b16 v174, v16 offset:35328
	ds_write_b16_d16_hi v174, v16 offset:39680
	v_lshlrev_b32_e32 v20, 16, v122
	v_and_b32_e32 v21, 0xffff0000, v122
	v_lshlrev_b32_e32 v18, 16, v123
	v_and_b32_e32 v19, 0xffff0000, v123
	v_lshlrev_b32_e32 v24, 16, v124
	v_and_b32_e32 v25, 0xffff0000, v124
	v_lshlrev_b32_e32 v22, 16, v125
	v_and_b32_e32 v23, 0xffff0000, v125
	v_mov_b32_e32 v16, v182
	v_mov_b32_e32 v17, v183
	v_sub_f32_e32 v21, v21, v16
	v_sub_f32_e32 v20, v20, v16
	v_sub_f32_e32 v19, v19, v16
	v_sub_f32_e32 v18, v18, v16
	v_pk_mul_f32 v[20:21], v[16:17], v[20:21] op_sel:[1,0]
	v_sub_f32_e32 v23, v23, v16
	v_sub_f32_e32 v22, v22, v16
	v_sub_f32_e32 v25, v25, v16
	v_sub_f32_e32 v24, v24, v16
	v_pk_mul_f32 v[18:19], v[16:17], v[18:19] op_sel:[1,0]
	v_pk_fma_f32 v[20:21], v[8:9], v[20:21], v[12:13]
	v_pk_mul_f32 v[24:25], v[16:17], v[24:25] op_sel:[1,0]
	v_pk_mul_f32 v[16:17], v[16:17], v[22:23] op_sel:[1,0]
	v_pk_fma_f32 v[18:19], v[10:11], v[18:19], v[14:15]
	v_pk_fma_f32 v[16:17], v[2:3], v[16:17], v[6:7]
	v_pk_fma_f32 v[22:23], v[0:1], v[24:25], v[4:5]
	v_cvt_pk_bf16_f32 v20, v20, v21
	v_cvt_pk_bf16_f32 v18, v18, v19
	v_cvt_pk_bf16_f32 v19, v22, v23
	v_cvt_pk_bf16_f32 v16, v16, v17
	ds_write_b16 v172, v20 offset:9216
	ds_write_b16_d16_hi v172, v20 offset:13568
	ds_write_b16 v172, v18 offset:17920
	ds_write_b16_d16_hi v172, v18 offset:22272
	ds_write_b16 v172, v19 offset:26624
	ds_write_b16_d16_hi v172, v19 offset:30976
	ds_write_b16 v172, v16 offset:35328
	ds_write_b16_d16_hi v172, v16 offset:39680
	s_waitcnt vmcnt(5)
	v_lshlrev_b32_e32 v20, 16, v118
	v_and_b32_e32 v21, 0xffff0000, v118
	v_lshlrev_b32_e32 v18, 16, v119
	v_and_b32_e32 v19, 0xffff0000, v119
	v_lshlrev_b32_e32 v24, 16, v120
	v_and_b32_e32 v25, 0xffff0000, v120
	v_lshlrev_b32_e32 v22, 16, v121
	v_and_b32_e32 v23, 0xffff0000, v121
	v_mov_b32_e32 v16, v184
	v_mov_b32_e32 v17, v185
	v_sub_f32_e32 v21, v21, v16
	v_sub_f32_e32 v20, v20, v16
	v_sub_f32_e32 v19, v19, v16
	v_sub_f32_e32 v18, v18, v16
	v_pk_mul_f32 v[20:21], v[16:17], v[20:21] op_sel:[1,0]
	v_sub_f32_e32 v23, v23, v16
	v_sub_f32_e32 v22, v22, v16
	v_sub_f32_e32 v25, v25, v16
	v_sub_f32_e32 v24, v24, v16
	v_pk_mul_f32 v[18:19], v[16:17], v[18:19] op_sel:[1,0]
	v_pk_fma_f32 v[20:21], v[8:9], v[20:21], v[12:13]
	v_pk_mul_f32 v[24:25], v[16:17], v[24:25] op_sel:[1,0]
	v_pk_mul_f32 v[16:17], v[16:17], v[22:23] op_sel:[1,0]
	v_pk_fma_f32 v[18:19], v[10:11], v[18:19], v[14:15]
	v_pk_fma_f32 v[16:17], v[2:3], v[16:17], v[6:7]
	v_pk_fma_f32 v[22:23], v[0:1], v[24:25], v[4:5]
	v_cvt_pk_bf16_f32 v20, v20, v21
	v_cvt_pk_bf16_f32 v18, v18, v19
	v_cvt_pk_bf16_f32 v19, v22, v23
	v_cvt_pk_bf16_f32 v16, v16, v17
	ds_write_b16 v170, v20 offset:9216
	ds_write_b16_d16_hi v170, v20 offset:13568
	ds_write_b16 v170, v18 offset:17920
	ds_write_b16_d16_hi v170, v18 offset:22272
	ds_write_b16 v170, v19 offset:26624
	ds_write_b16_d16_hi v170, v19 offset:30976
	ds_write_b16 v170, v16 offset:35328
	ds_write_b16_d16_hi v170, v16 offset:39680
	s_waitcnt vmcnt(4)
	v_lshlrev_b32_e32 v20, 16, v114
	v_and_b32_e32 v21, 0xffff0000, v114
	v_lshlrev_b32_e32 v18, 16, v115
	v_and_b32_e32 v19, 0xffff0000, v115
	v_mov_b32_e32 v16, v186
	v_mov_b32_e32 v17, v187
	v_sub_f32_e32 v19, v19, v16
	v_sub_f32_e32 v18, v18, v16
	v_sub_f32_e32 v21, v21, v16
	v_sub_f32_e32 v20, v20, v16
	v_lshlrev_b32_e32 v22, 16, v116
	v_and_b32_e32 v23, 0xffff0000, v116
	v_lshlrev_b32_e32 v24, 16, v117
	v_and_b32_e32 v25, 0xffff0000, v117
	v_pk_mul_f32 v[20:21], v[16:17], v[20:21] op_sel:[1,0]
	v_pk_mul_f32 v[18:19], v[16:17], v[18:19] op_sel:[1,0]
	v_pk_fma_f32 v[8:9], v[8:9], v[20:21], v[12:13]
	v_pk_fma_f32 v[10:11], v[10:11], v[18:19], v[14:15]
	v_sub_f32_e32 v13, v25, v16
	v_sub_f32_e32 v12, v24, v16
	v_sub_f32_e32 v15, v23, v16
	v_sub_f32_e32 v14, v22, v16
	v_pk_mul_f32 v[14:15], v[16:17], v[14:15] op_sel:[1,0]
	v_pk_mul_f32 v[12:13], v[16:17], v[12:13] op_sel:[1,0]
	v_pk_fma_f32 v[0:1], v[0:1], v[14:15], v[4:5]
	v_pk_fma_f32 v[2:3], v[2:3], v[12:13], v[6:7]
	v_cvt_pk_bf16_f32 v4, v8, v9
	v_cvt_pk_bf16_f32 v0, v0, v1
	v_cvt_pk_bf16_f32 v1, v2, v3
	v_cvt_pk_bf16_f32 v5, v10, v11
	ds_write_b16 v168, v4 offset:9216
	ds_write_b16_d16_hi v168, v4 offset:13568
	ds_write_b16 v168, v5 offset:17920
	ds_write_b16_d16_hi v168, v5 offset:22272
	ds_write_b16 v168, v0 offset:26624
	ds_write_b16_d16_hi v168, v0 offset:30976
	ds_write_b16 v168, v1 offset:35328
	ds_write_b16_d16_hi v168, v1 offset:39680
	v_lshl_add_u64 v[0:1], v[156:157], 0, v[64:65]
	global_load_dwordx4 v[126:129], v[0:1], off
	v_lshl_add_u64 v[0:1], v[158:159], 0, v[64:65]
	global_load_dwordx4 v[122:125], v[0:1], off
	v_lshl_add_u64 v[0:1], v[160:161], 0, v[64:65]
	global_load_dwordx4 v[118:121], v[0:1], off
	v_lshl_add_u64 v[0:1], v[154:155], 0, v[64:65]
	global_load_dwordx4 v[114:117], v[0:1], off
	s_and_b64 vcc, exec, s[38:39]
	v_mov_b32_e32 v0, 0
	v_mov_b32_e32 v1, 0
	v_mov_b32_e32 v2, 0
	v_mov_b32_e32 v3, 0
	v_mov_b32_e32 v4, 0
	v_mov_b32_e32 v5, 0
	v_mov_b32_e32 v6, 0
	v_mov_b32_e32 v7, 0
	v_mov_b32_e32 v8, 0
	v_mov_b32_e32 v9, 0
	v_mov_b32_e32 v10, 0
	v_mov_b32_e32 v11, 0
	v_mov_b32_e32 v12, 0
	v_mov_b32_e32 v13, 0
	v_mov_b32_e32 v14, 0
	v_mov_b32_e32 v15, 0
	s_waitcnt lgkmcnt(0)
	s_barrier
; #define LAS __attribute__((address_space(3)))
;     ...
;         const int d = 32 * dblk + r32;
;         const LAS unsigned char* ab = lds + BA_VNT + ((d & 7) * 16 + (d >> 3)) * 272 + hi * 16;
;         f32x16 acc[2];
; #pragma unroll
;         for (int j = 0; j < 2; ++j) {
;             const int tb = 2 * tbp + j;
; #pragma unroll
;             for (int r = 0; r < 16; ++r) acc[j][r] = 0.f;
; #pragma unroll
;             for (int ks = 0; ks < 8; ++ks) if (ks < 2 * (tb + 1)) {
;                 const bf16x8 af = *(const LAS bf16x8*)(ab + ks * 32);
;                 acc[j] = __builtin_amdgcn_mfma_f32_32x32x16_bf16(af, wf[j][ks], acc[j], 0, 0, 0);
	v_add_u32_e32 v250, v139, v140
	ds_read_b128 v[206:209], v250 offset:9216
	ds_read_b128 v[210:213], v250 offset:9248
	ds_read_b128 v[214:217], v250 offset:9280
	ds_read_b128 v[218:221], v250 offset:9312
	ds_read_b128 v[222:225], v250 offset:9344
	ds_read_b128 v[226:229], v250 offset:9376
	ds_read_b128 v[242:245], v250 offset:9408
	ds_read_b128 v[246:249], v250 offset:9440
	s_waitcnt lgkmcnt(0)
	s_cbranch_vccnz .LBB0_512
	v_mfma_f32_32x32x16_bf16 v[0:15], v[206:209], v[110:113], 0
